# mixer work queue per XCD: workgroups of an XCD take the items of two (batch, head) K/V streams so the streams share an L2; same items, same per-item work
# speedup vs baseline: 1.0006x; 1.0002x over previous
; DI void phase_prep(const Prm& p, int tid, int lane, int wid) {
;     const int gt = blockIdx.x * 512 + tid, ngt = gridDim.x * 512, gw = blockIdx.x * 8 + wid, ngw = gridDim.x * 8;
;     unsigned char* ws = p.ws;
;     if (gt == 0) { ((unsigned*)(ws + W_CTR))[0] = 0u; ((unsigned*)(ws + W_CTR))[64] = 0u; }
.LBB0_17:
	v_mov_b32_e32 v8, v212
	s_lshl_b32 s4, s3, 9
	v_writelane_b32 v247, s4, 8
	v_add_u32_e32 v0, s4, v8
	v_readfirstlane_b32 s2, v8
	v_cmp_eq_u32_e32 vcc, 0, v0
	s_and_saveexec_b64 s[4:5], vcc
	s_cbranch_execz .LBB0_19
	v_mov_b32_e32 v1, 0x100000
	v_mov_b32_e32 v2, 0
	global_store_dword v1, v2, s[34:35]
	global_store_dword v1, v2, s[34:35] offset:256
	global_store_dword v1, v2, s[34:35] offset:512
	global_store_dword v1, v2, s[34:35] offset:576
	global_store_dword v1, v2, s[34:35] offset:640
	global_store_dword v1, v2, s[34:35] offset:704
	global_store_dword v1, v2, s[34:35] offset:768
	global_store_dword v1, v2, s[34:35] offset:832
	global_store_dword v1, v2, s[34:35] offset:896
	global_store_dword v1, v2, s[34:35] offset:960

; DI void phase_mix(const Prm& p, unsigned char* lds, int tid0, int wid, int lane0) {
;     unsigned char* ws = p.ws; const bf16_t* Q = (const bf16_t*)(ws + W_Q); const bf16_t* KN = (const bf16_t*)(ws + W_KN); const bf16_t* VT = (const bf16_t*)(ws + W_VT);
;     const bf16_t* HP = (const bf16_t*)(ws + W_HP);
;     const bf16_t* QS = (const bf16_t*)(ws + W_QS); bf16_t* OL = (bf16_t*)(ws + W_OL); bf16_t* O = (bf16_t*)(ws + W_XN);
;     unsigned* ctr = (unsigned*)(ws + W_CTR); unsigned* sh = (unsigned*)(lds + LDS_BYTES - 64);
;     if ((MIX_MASK & 4) && blockIdx.x < 16) gdn_scan_unit(p, lds, 0, blockIdx.x >> 2, blockIdx.x & 3, tid0, wid, lane0);
.LBB0_1825:
	s_add_u32 s44, s34, 0x100000
	s_addc_u32 s45, s35, 0
	s_getreg_b32 s100, hwreg(HW_REG_XCC_ID, 0, 4)
	s_and_b32 s100, s100, 7
	s_lshl_b32 s101, s100, 6
	s_add_u32 s44, s44, s101
	s_addc_u32 s45, s45, 0
	s_add_u32 s44, s44, 0x200
	s_addc_u32 s45, s45, 0
	s_add_u32 s50, s34, 0x47cbd00
	s_addc_u32 s51, s35, 0
	s_cmp_lt_u32 s10, 64
	s_cselect_b64 s[52:53], -1, 0
	s_cmp_lt_i32 s11, 4
	s_cselect_b64 s[42:43], -1, 0
	s_ashr_i32 s6, s10, 7
	s_lshl_b32 s0, s6, 8
	s_lshl_b32 s41, s11, 7
	s_ashr_i32 s1, s0, 31
	s_or_b32 s58, s41, 64
	s_add_i32 s71, s6, 1
	s_and_b32 s84, s36, 32
	s_lshl_b64 s[0:1], s[0:1], 1
	s_add_u32 s62, s2, s0
	s_mulk_i32 s6, 0xc0
	s_addc_u32 s63, s33, s1
	s_ashr_i32 s7, s6, 31
	s_lshl_b64 s[6:7], s[6:7], 1
	s_add_u32 s64, s66, s6
	s_addc_u32 s65, s67, s7
	s_add_u32 s0, s34, s0
	s_addc_u32 s1, s35, s1
	s_add_u32 s74, s0, 0x1dec3800
	s_addc_u32 s75, s1, 0
	s_add_u32 s33, s34, 0x1a61a800
	s_addc_u32 s59, s35, 0
	s_add_u32 s72, s30, 0xb3a6000
	s_addc_u32 s73, s31, 0
	s_add_i32 s93, 0, 0x23fc0
	s_movk_i32 s76, 0xff00
	s_movk_i32 s78, 0xfe00
	s_mov_b32 s47, 0
	v_cmp_eq_u32_e64 s[4:5], 0, v180
	s_waitcnt vmcnt(13)
	v_mov_b32_e32 v1, 0
	s_movk_i32 s94, 0x600
	s_mov_b32 s95, 0x2aaaaaab
	s_movk_i32 s96, 0x1600
	s_mov_b32 s77, -1
	s_mov_b32 s97, 0x11200
	s_movk_i32 s86, 0x190
	s_movk_i32 s49, 0x88
	s_movk_i32 s89, 0x6400
	s_mov_b32 s92, 0xff800000
	s_movk_i32 s87, 0x110
	s_movk_i32 s40, 0x90
	s_movk_i32 s48, 0xc8
	s_movk_i32 s85, 0x44
	s_add_i32 s88, 0, 0x10c00
	s_movk_i32 s54, 0x290
	s_mov_b32 s37, 0x66666667
	s_mov_b32 s79, -1
	s_movk_i32 s55, 0xfd72
	v_mov_b32_e32 v181, s93
	v_mov_b32_e32 v214, 0xffffff80
	v_mov_b32_e32 v215, 0xff800000
	s_branch .LBB0_1829

;     ...
;     auto gload = [&](int t) { const int rb = t == 0 ? r0 : r1 + 64 * (t - 1);
; #pragma unroll
;         for (int i = 0; i < NKC; ++i) { const int e = tid + 512 * i, row = e / CPR, cc = e % CPR;
; DI void phase_mix(const Prm& p, unsigned char* lds, int tid0, int wid, int lane0) {
;     ...
;     for (;;) {
;         __syncthreads();
;         if (tid0 == 0) sh[0] = atomicAdd(ctr, 1u);
;         __syncthreads();
;         const int it = (int)sh[0];
;         int lane = lane0, tid = tid0; asm volatile("" : "+v"(lane), "+v"(tid)); const int lr = lane & 31;
;         if (it >= 720) break;
;         if ((MIX_MASK & 1) && it < 64) {
;             const int sb = it >> 1, ps = it & 1, hq = wid >> 1, qrow = sb * 64 + 32 * (wid & 1) + lr;
;             attn_unit<256, 2, true>(lds, QS + (size_t)qrow * 1024 + hq * 256, Q + (size_t)(ROW_S + qrow) * 768 + hq * 192 + 128, HP + (size_t)(ROW_S + 64 * sb) * NPJ + C_CKV, NPJ, HP + (size_t)(ROW_S + 64 * sb) * NPJ + C_KR, NPJ,
;                            nullptr, 0, 0, 16, 34, 33, OL + (size_t)qrow * 1024 + hq * 256 + 128 * ps, true, tid, lane, p.cache_ckv + (size_t)sb * 2064 * 256, p.cache_kr + (size_t)sb * 2064 * 64, ps);
;         } else if ((MIX_MASK & 2) && it >= 64 && it < 576) {
;             const int j = it - 64, qb = 31 - (j >> 4), bh = j & 15, b = bh >> 2, h = bh & 3; const int row = b * 8192 + 256 * qb + 32 * wid + lr;
;             attn_unit<128, 1, false>(lds, Q + (size_t)row * 768 + h * 192, Q + (size_t)row * 768 + h * 192 + 128, KN + h * 128, 512, HP + C_KR, NPJ, VT + (size_t)(h * 128) * M, M,
;                            ROW_META + 16 * b, b * 8192, 4 * qb + 5, 4 * qb + (wid >> 1) + 1, O + (size_t)row * D + 512 + h * 128, true, tid, lane);
;         } else if ((MIX_MASK & 4) && it >= 576 && it < 704) {
;             const int j = it - 576; gdn_scan_unit(p, lds, 1, j >> 2, j & 3, tid, wid, lane);
;         } else if ((MIX_MASK & 8) && it >= 704) {
;             const int j = it - 704, b = j >> 2, h = j & 3; const int row = ROW_META + 16 * b + lr;
;             attn_unit<128, 1, false>(lds, Q + (size_t)row * 768 + h * 192, Q + (size_t)row * 768 + h * 192 + 128, KN + h * 128, 512, HP + C_KR, NPJ, VT + (size_t)(h * 128) * M, M,
;                            ROW_META + 16 * b, b * 8192, 1, wid == 0 ? 0 : -1, O + (size_t)row * D + 512 + h * 128, wid == 0 && lane < 16 || (wid == 0 && lane >= 32 && lane < 48), tid, lane);
.LBB0_1833:
	s_or_b64 exec, exec, s[0:1]
	s_waitcnt lgkmcnt(0)
	s_barrier
	ds_read_b32 v0, v181
	s_movk_i32 s0, 0x59
	v_mov_b32_e32 v209, v213
	v_mov_b32_e32 v182, v180
	s_waitcnt lgkmcnt(0)
	v_cmp_lt_i32_e32 vcc, s0, v0
	v_readfirstlane_b32 s2, v0
	s_mov_b64 s[0:1], -1
	s_cbranch_vccnz .LBB0_1828
	v_and_b32_e32 v208, 31, v209
	s_cmp_lt_u32 s2, 8
	s_cbranch_scc0 .Lxq_1
	s_lshr_b32 s98, s2, 1
	s_lshl_b32 s98, s98, 3
	s_add_i32 s98, s98, s100
	s_lshl_b32 s98, s98, 1
	s_and_b32 s2, s2, 1
	s_add_i32 s2, s2, s98
	s_branch .Lxq_done
.Lxq_1:
	s_cmp_lt_u32 s2, 0x48
	s_cbranch_scc0 .Lxq_2
	s_sub_i32 s98, s2, 8
	s_and_b32 s99, s98, 1
	s_lshr_b32 s98, s98, 1
	s_lshl_b32 s98, s98, 4
	s_lshl_b32 s99, s99, 3
	s_add_i32 s98, s98, s99
	s_add_i32 s98, s98, s100
	s_add_i32 s2, s98, 64
	s_branch .Lxq_done
.Lxq_2:
	s_cmp_lt_u32 s2, 0x58
	s_cbranch_scc0 .Lxq_3
	s_sub_i32 s98, s2, 0x48
	s_and_b32 s99, s98, 3
	s_lshr_b32 s98, s98, 2
	s_lshl_b32 s98, s98, 3
	s_add_i32 s98, s98, s100
	s_lshl_b32 s98, s98, 2
	s_add_i32 s98, s98, s99
	s_add_i32 s2, s98, 0x240
	s_branch .Lxq_done
.Lxq_3:
	s_sub_i32 s98, s2, 0x58
	s_lshl_b32 s99, s100, 1
	s_add_i32 s98, s98, s99
	s_add_i32 s2, s98, 0x2c0
.Lxq_done:
	s_cmp_gt_i32 s2, 63
	s_cbranch_scc0 .LBB0_1932
	s_cmpk_gt_u32 s2, 0x23f
	s_cbranch_scc0 .LBB0_1865
	s_cmpk_gt_u32 s2, 0x2bf
	s_cbranch_scc0 .LBB0_1855
	s_lshl_b32 s0, s2, 2
	s_and_b32 s8, s0, 0x7ffffff0
	s_addk_i32 s8, 0x7d00
	s_and_b32 s9, s2, 3
	s_waitcnt vmcnt(9)
	v_add_u32_e32 v74, s8, v208
	v_mov_b64_e32 v[2:3], s[66:67]
	v_ashrrev_i32_e32 v70, 5, v209
	v_mad_u64_u32 v[2:3], s[0:1], v74, s94, v[2:3]
	s_mul_i32 s46, s9, 0x180
	v_lshlrev_b32_e32 v14, 3, v70
	v_lshl_add_u64 v[2:3], v[2:3], 0, s[46:47]
	v_ashrrev_i32_e32 v15, 31, v14
	v_lshl_add_u64 v[6:7], v[14:15], 1, v[2:3]
	global_load_dwordx4 v[2:5], v[6:7], off
	global_load_dwordx4 v[58:61], v[6:7], off offset:32
	global_load_dwordx4 v[54:57], v[6:7], off offset:64
	global_load_dwordx4 v[50:53], v[6:7], off offset:96
	global_load_dwordx4 v[46:49], v[6:7], off offset:128
	global_load_dwordx4 v[42:45], v[6:7], off offset:160
	global_load_dwordx4 v[38:41], v[6:7], off offset:192
	global_load_dwordx4 v[34:37], v[6:7], off offset:224
	global_load_dwordx4 v[30:33], v[6:7], off offset:256
	global_load_dwordx4 v[26:29], v[6:7], off offset:288
	global_load_dwordx4 v[22:25], v[6:7], off offset:320
	global_load_dwordx4 v[18:21], v[6:7], off offset:352
	v_mul_hi_i32 v0, v182, s95
	v_lshrrev_b32_e32 v6, 31, v0
	v_ashrrev_i32_e32 v0, 2, v0
	v_add_u32_e32 v15, v0, v6
	s_lshl_b32 s0, s9, 8
	v_mul_lo_u32 v0, v15, 24
	s_add_u32 s0, s60, s0
	v_sub_u32_e32 v0, v182, v0
	v_add_u32_e32 v6, s8, v15
	s_addc_u32 s1, s61, 0
	v_cmp_lt_i32_e32 vcc, 15, v0
	v_ashrrev_i32_e32 v7, 31, v6
	v_lshlrev_b32_e32 v16, 3, v0
	s_and_saveexec_b64 s[6:7], vcc
	s_xor_b64 s[6:7], exec, s[6:7]
	v_mov_b64_e32 v[8:9], s[50:51]
	v_mad_i64_i32 v[6:7], s[10:11], v6, s96, v[8:9]
	v_mov_b32_e32 v17, v1
	v_lshl_add_u64 v[6:7], v[16:17], 1, v[6:7]
	v_lshl_add_u64 v[8:9], v[6:7], 0, s[76:77]
	s_andn2_saveexec_b64 s[6:7], s[6:7]
	v_lshlrev_b64 v[6:7], 10, v[6:7]
	v_lshl_add_u64 v[6:7], s[0:1], 0, v[6:7]
	v_ashrrev_i32_e32 v17, 31, v16
	v_lshl_add_u64 v[8:9], v[16:17], 1, v[6:7]
	s_or_b64 exec, exec, s[6:7]
	global_load_dwordx4 v[6:9], v[8:9], off
	v_add_u32_e32 v71, 0x200, v182
	v_mul_hi_i32 v0, v71, s95
	v_lshrrev_b32_e32 v10, 31, v0
	v_ashrrev_i32_e32 v0, 2, v0
	v_add_u32_e32 v17, v0, v10
	v_mul_lo_u32 v0, v17, 24
	v_sub_u32_e32 v0, v71, v0
	v_add_u32_e32 v10, s8, v17
	v_cmp_lt_i32_e32 vcc, 15, v0
	v_ashrrev_i32_e32 v11, 31, v10
	v_lshlrev_b32_e32 v62, 3, v0
	s_and_saveexec_b64 s[6:7], vcc
	s_xor_b64 s[6:7], exec, s[6:7]
	v_mov_b64_e32 v[12:13], s[50:51]
	v_mad_i64_i32 v[10:11], s[10:11], v10, s96, v[12:13]
	v_mov_b32_e32 v63, v1
	v_lshl_add_u64 v[10:11], v[62:63], 1, v[10:11]
	v_lshl_add_u64 v[12:13], v[10:11], 0, s[76:77]
	s_andn2_saveexec_b64 s[6:7], s[6:7]
	v_lshlrev_b64 v[10:11], 10, v[10:11]
	v_lshl_add_u64 v[10:11], s[0:1], 0, v[10:11]
	v_ashrrev_i32_e32 v63, 31, v62
	v_lshl_add_u64 v[12:13], v[62:63], 1, v[10:11]
	s_or_b64 exec, exec, s[6:7]
	global_load_dwordx4 v[10:13], v[12:13], off
	v_add_u32_e32 v0, 0x400, v182
	v_mul_hi_i32 v63, v0, s95
	v_lshrrev_b32_e32 v64, 31, v63
	v_ashrrev_i32_e32 v63, 2, v63
	v_add_u32_e32 v63, v63, v64
	v_mul_lo_u32 v64, v63, 24
	v_sub_u32_e32 v0, v0, v64
	v_add_u32_e32 v68, s8, v63
	v_cmp_lt_i32_e32 vcc, 15, v0
	v_ashrrev_i32_e32 v69, 31, v68
	v_lshlrev_b32_e32 v64, 3, v0
	s_and_saveexec_b64 s[6:7], vcc
	s_xor_b64 s[6:7], exec, s[6:7]
	v_mov_b64_e32 v[66:67], s[50:51]
	v_mad_i64_i32 v[66:67], s[10:11], v68, s96, v[66:67]
	v_mov_b32_e32 v65, v1
	v_lshl_add_u64 v[66:67], v[64:65], 1, v[66:67]
	v_lshl_add_u64 v[66:67], v[66:67], 0, s[76:77]
	s_andn2_saveexec_b64 s[6:7], s[6:7]
	v_lshlrev_b64 v[66:67], 10, v[68:69]
	v_lshl_add_u64 v[66:67], s[0:1], 0, v[66:67]
	v_ashrrev_i32_e32 v65, 31, v64
	v_lshl_add_u64 v[66:67], v[64:65], 1, v[66:67]
	s_or_b64 exec, exec, s[6:7]
	s_lshl_b32 s6, s9, 7
	s_mul_i32 s0, s6, 0x11200
	v_readlane_b32 s10, v246, 14
	v_readlane_b32 s11, v246, 15
	s_add_u32 s0, s10, s0
	s_addc_u32 s1, s11, 0
	v_ashrrev_i32_e32 v65, 3, v182
	v_mov_b64_e32 v[72:73], s[0:1]
	s_waitcnt vmcnt(22)
	v_mad_i64_i32 v[76:77], s[0:1], v65, s97, v[72:73]
	s_lshl_b32 s46, s8, 1
	v_lshlrev_b32_e32 v0, 4, v182
	v_ashrrev_i32_e32 v71, 3, v71
	v_lshl_add_u64 v[76:77], v[76:77], 0, s[46:47]
	v_and_b32_e32 v0, 0x70, v0
	v_mad_i64_i32 v[72:73], s[0:1], v71, s97, v[72:73]
	v_lshl_add_u64 v[76:77], v[76:77], 0, v[0:1]
	v_lshl_add_u64 v[72:73], v[72:73], 0, s[46:47]
	global_load_dwordx4 v[66:69], v[66:67], off
	v_lshl_add_u64 v[72:73], v[72:73], 0, v[0:1]
	global_load_dwordx4 v[78:81], v[76:77], off
	global_load_dwordx4 v[82:85], v[72:73], off
	v_mul_lo_u32 v15, v15, s86
	v_lshlrev_b32_e32 v16, 1, v16
	v_mul_lo_u32 v17, v17, s86
	v_lshlrev_b32_e32 v62, 1, v62
	v_mul_lo_u32 v63, v63, s86
	v_lshlrev_b32_e32 v64, 1, v64
	v_add3_u32 v15, 0, v15, v16
	v_add3_u32 v16, 0, v17, v62
	v_add3_u32 v17, 0, v63, v64
	v_mul_lo_u32 v62, v65, s49
	v_mul_lo_u32 v63, v71, s49
	v_lshlrev_b32_e32 v76, 2, v70
	s_waitcnt vmcnt(4)
	ds_write_b128 v15, v[6:9]
	s_waitcnt vmcnt(3)
	ds_write_b128 v16, v[10:13]
	v_add_u32_e32 v6, 0, v62
	v_add_u32_e32 v7, 0, v63
	s_and_b64 vcc, exec, s[52:53]
	v_add3_u32 v6, v6, v0, s89
	v_add3_u32 v0, v7, v0, s89
	s_waitcnt vmcnt(2)
	ds_write_b128 v17, v[66:69]
	s_waitcnt vmcnt(1)
	ds_write2_b64 v6, v[78:79], v[80:81] offset1:1
	s_waitcnt vmcnt(0)
	ds_write2_b64 v0, v[82:83], v[84:85] offset1:1
	s_waitcnt lgkmcnt(0)
	s_barrier
; #define MFMA32(a, b, c) __builtin_amdgcn_mfma_f32_32x32x16_bf16((a), (b), (c), 0, 0, 0)
;     ...
;     auto compute = [&](const bf16_t* Kt, const bf16_t* Vt, int t) {
;         f32x16 s0, s1;
; #pragma unroll
;         for (int i = 0; i < 16; ++i) { s0[i] = 0.f; s1[i] = 0.f; }
; #pragma unroll
;         for (int ks = 0; ks < NKS; ++ks) { const bf16x8 a0 = *(const bf16x8*)(Kt + lr * KSTR + 16 * ks + 8 * hi), a1 = *(const bf16x8*)(Kt + (32 + lr) * KSTR + 16 * ks + 8 * hi);
;             bf16x8 qq;
;             if (QREG == 1) qq = qf[ks];
;             else if (QREG == 2) qq = 16 * ks < DN ? qf[ks < NQF ? ks : 0] : *(const bf16x8*)(qr_row + (16 * ks - DN) + 8 * hi);
;             else qq = 16 * ks < DN ? *(const bf16x8*)(qa_row + 16 * ks + 8 * hi) : qf[(16 * ks - DN) / 16 < NQF ? (16 * ks - DN) / 16 : 0];
;             s0 = MFMA32(a0, qq, s0); s1 = MFMA32(a1, qq, s1);
;             if ((ks & 3) == 3) __builtin_amdgcn_sched_barrier(0); }
;         if (t == 0) {
; #pragma unroll
;             for (int i = 0; i < 16; ++i) { if (i >= 8) s0[i] = -INFINITY; s1[i] = -INFINITY; } }
;         float mx = s0[0];
; #pragma unroll
;         for (int i = 1; i < 16; ++i) mx = fmaxf(mx, s0[i]);
; #pragma unroll
;         for (int i = 0; i < 16; ++i) mx = fmaxf(mx, s1[i]);
;         mx = xhalf_max(mx);
;         const float mnew = fmaxf(mrun, mx), alpha = __builtin_amdgcn_exp2f(mrun - mnew);
;         const bool resc = __builtin_amdgcn_ballot_w64(mnew != mrun) != 0ull; mrun = mnew;
;         float ps = 0.f;
; #pragma unroll
;         for (int i = 0; i < 16; ++i) { s0[i] = __builtin_amdgcn_exp2f(s0[i] - mnew); s1[i] = __builtin_amdgcn_exp2f(s1[i] - mnew); ps += s0[i] + s1[i]; }
;         lrun = lrun * alpha + ps;
;         if (resc) {
; #pragma unroll
;             for (int d = 0; d < 4; ++d)
; #pragma unroll
;                 for (int i = 0; i < 16; ++i) oacc[d][i] *= alpha; }
;         bf16x8 pf[4]; pf[0] = packs(s0, 0); pf[1] = packs(s0, 1); pf[2] = packs(s1, 0); pf[3] = packs(s1, 1);
; #pragma unroll
;         for (int d = 0; d < 4; ++d)
; #pragma unroll
;             for (int ks = 0; ks < 4; ++ks) { const bf16x8 a = ld_perm(Vt + (32 * d + lr) * VSTR + 16 * ks + 4 * hi); oacc[d] = MFMA32(a, pf[ks], oacc[d]); if (ks == 3) __builtin_amdgcn_sched_barrier(0); }
	s_cbranch_vccz .LBB0_1851
	v_mad_u32_u24 v75, v208, s86, 0
	v_lshl_add_u32 v0, v14, 1, v75
	ds_read_b128 v[6:9], v0
	ds_read_b128 v[62:65], v0 offset:32
	s_waitcnt lgkmcnt(1)
	v_mfma_f32_32x32x16_bf16 v[2:17], v[6:9], v[2:5], 0
	s_waitcnt lgkmcnt(0)
	v_mfma_f32_32x32x16_bf16 v[2:17], v[62:65], v[58:61], v[2:17]
	ds_read_b128 v[58:61], v0 offset:64
	s_waitcnt lgkmcnt(0)
	v_mfma_f32_32x32x16_bf16 v[2:17], v[58:61], v[54:57], v[2:17]
	ds_read_b128 v[54:57], v0 offset:96
	s_waitcnt lgkmcnt(0)
	v_mfma_f32_32x32x16_bf16 v[2:17], v[54:57], v[50:53], v[2:17]
	ds_read_b128 v[50:53], v0 offset:128
	s_waitcnt lgkmcnt(0)
	v_mfma_f32_32x32x16_bf16 v[2:17], v[50:53], v[46:49], v[2:17]
	ds_read_b128 v[46:49], v0 offset:160
	s_waitcnt lgkmcnt(0)
	v_mfma_f32_32x32x16_bf16 v[2:17], v[46:49], v[42:45], v[2:17]
	ds_read_b128 v[42:45], v0 offset:192
	s_waitcnt lgkmcnt(0)
	v_mfma_f32_32x32x16_bf16 v[2:17], v[42:45], v[38:41], v[2:17]
	ds_read_b128 v[38:41], v0 offset:224
	s_waitcnt lgkmcnt(0)
	v_mfma_f32_32x32x16_bf16 v[2:17], v[38:41], v[34:37], v[2:17]
	ds_read_b128 v[34:37], v0 offset:256
	s_waitcnt lgkmcnt(0)
	v_mfma_f32_32x32x16_bf16 v[2:17], v[34:37], v[30:33], v[2:17]
	ds_read_b128 v[30:33], v0 offset:288
	s_waitcnt lgkmcnt(0)
	v_mfma_f32_32x32x16_bf16 v[2:17], v[30:33], v[26:29], v[2:17]
	ds_read_b128 v[26:29], v0 offset:320
	s_waitcnt lgkmcnt(0)
	v_mfma_f32_32x32x16_bf16 v[2:17], v[26:29], v[22:25], v[2:17]
	ds_read_b128 v[22:25], v0 offset:352
	s_waitcnt lgkmcnt(0)
	v_mfma_f32_32x32x16_bf16 v[2:17], v[22:25], v[18:21], v[2:17]
	s_nop 11
	v_max3_f32 v0, v2, v3, v4
	v_max3_f32 v0, v0, v5, v6
	v_max3_f32 v0, v0, v7, v8
	v_max3_f32 v0, v0, v9, s92
	v_mov_b32_e32 v10, v0
	s_nop 1
	v_permlane32_swap_b32_e32 v0, v10
	v_max3_f32 v0, v0, v10, s92
	v_sub_f32_e32 v10, 0xff800000, v0
	v_sub_f32_e32 v2, v2, v0
	v_exp_f32_e32 v22, v2
	v_exp_f32_e32 v18, v10
	v_sub_f32_e32 v3, v3, v0
	v_exp_f32_e32 v23, v3
	v_cmp_neq_f32_e32 vcc, s92, v0
	v_add_f32_e32 v2, v22, v18
	v_add_f32_e32 v2, 0, v2
	v_add_f32_e32 v3, v23, v18
	v_add_f32_e32 v2, v3, v2
	v_sub_f32_e32 v3, v4, v0
	v_exp_f32_e32 v24, v3
	v_cvt_pk_bf16_f32 v66, v18, v18
	s_cmp_lg_u64 vcc, 0
	s_cselect_b64 vcc, -1, 0
	v_add_f32_e32 v3, v24, v18
	v_add_f32_e32 v2, v3, v2
	v_sub_f32_e32 v3, v5, v0
	v_exp_f32_e32 v25, v3
	v_cvt_pk_bf16_f32 v70, v22, v23
	v_mov_b32_e32 v67, v66
	v_mov_b32_e32 v68, v66
	v_add_f32_e32 v3, v25, v18
	v_add_f32_e32 v2, v3, v2
	v_sub_f32_e32 v3, v6, v0
	v_exp_f32_e32 v26, v3
	v_cvt_pk_bf16_f32 v71, v24, v25
	v_mov_b32_e32 v69, v66
	v_add_f32_e32 v3, v26, v18
	v_add_f32_e32 v4, v3, v2
	v_sub_f32_e32 v2, v7, v0
	v_exp_f32_e32 v21, v2
	v_sub_f32_e32 v2, v8, v0
	v_exp_f32_e32 v20, v2
	v_sub_f32_e32 v0, v9, v0
	v_cvt_pk_bf16_f32 v72, v26, v21
	v_pk_add_f32 v[2:3], v[20:21], v[18:19] op_sel_hi:[1,0]
	v_exp_f32_e32 v19, v0
	v_add_f32_e32 v3, v3, v4
	v_add_f32_e32 v4, v2, v3
	v_pk_add_f32 v[2:3], v[18:19], v[18:19] op_sel_hi:[1,0]
	s_nop 0
	v_add_f32_e32 v0, v3, v4
	v_add_f32_e32 v0, v2, v0
	v_add_f32_e32 v0, v2, v0
	v_add_f32_e32 v0, v2, v0
	v_add_f32_e32 v0, v2, v0
	v_add_f32_e32 v0, v2, v0
	v_add_f32_e32 v0, v2, v0
	v_add_f32_e32 v0, v2, v0
	v_add_f32_e32 v0, v2, v0
	v_mul_f32_e32 v2, 0, v18
	v_fmac_f32_e32 v0, 0, v18
	v_cvt_pk_bf16_f32 v73, v20, v19
	v_mul_i32_i24_e32 v18, 0xfffffef8, v208
	v_lshlrev_b32_e32 v19, 1, v76
	v_add3_u32 v75, v75, v18, v19
	v_add_u32_e32 v42, 0x6000, v75
	ds_read2_b64 v[34:37], v42 offset0:128 offset1:130
	ds_read2_b64 v[38:41], v42 offset0:132 offset1:134
	v_cndmask_b32_e32 v2, 0, v2, vcc
	v_mov_b32_e32 v3, v2
	v_mov_b32_e32 v4, v2
	v_mov_b32_e32 v5, v2
	v_mov_b32_e32 v6, v2
	v_mov_b32_e32 v7, v2
	v_mov_b32_e32 v8, v2
	v_mov_b32_e32 v9, v2
	v_mov_b32_e32 v10, v2
	v_mov_b32_e32 v11, v2
	v_mov_b32_e32 v12, v2
	v_mov_b32_e32 v13, v2
	v_mov_b32_e32 v14, v2
	v_mov_b32_e32 v15, v2
	v_mov_b32_e32 v16, v2
	v_mov_b32_e32 v17, v2
	s_waitcnt lgkmcnt(1)
	s_nop 0
	v_mfma_f32_32x32x16_bf16 v[18:33], v[34:37], v[70:73], v[2:17]
	ds_read2_b64 v[34:37], v42 offset0:136 offset1:138
	s_waitcnt lgkmcnt(1)
	v_mfma_f32_32x32x16_bf16 v[18:33], v[38:41], v[66:69], v[18:33]
	s_waitcnt lgkmcnt(0)
	v_mfma_f32_32x32x16_bf16 v[18:33], v[34:37], v[66:69], v[18:33]
	ds_read2_b64 v[34:37], v42 offset0:140 offset1:142
	s_waitcnt lgkmcnt(0)
	v_mfma_f32_32x32x16_bf16 v[18:33], v[34:37], v[66:69], v[18:33]
	v_add_u32_e32 v38, 0x7000, v75
	ds_read2_b64 v[34:37], v38 offset0:160 offset1:162
	s_waitcnt lgkmcnt(0)
	v_mfma_f32_32x32x16_bf16 v[50:65], v[34:37], v[70:73], v[2:17]
	ds_read2_b64 v[34:37], v38 offset0:164 offset1:166
	s_waitcnt lgkmcnt(0)
	v_mfma_f32_32x32x16_bf16 v[50:65], v[34:37], v[66:69], v[50:65]
	ds_read2_b64 v[34:37], v38 offset0:168 offset1:170
	s_waitcnt lgkmcnt(0)
	v_mfma_f32_32x32x16_bf16 v[50:65], v[34:37], v[66:69], v[50:65]
	ds_read2_b64 v[34:37], v38 offset0:172 offset1:174
	s_waitcnt lgkmcnt(0)
	v_mfma_f32_32x32x16_bf16 v[50:65], v[34:37], v[66:69], v[50:65]
	v_add_u32_e32 v77, 0x8000, v75
	ds_read2_b64 v[78:81], v77 offset0:192 offset1:194
	s_waitcnt lgkmcnt(0)
	v_mfma_f32_32x32x16_bf16 v[34:49], v[78:81], v[70:73], v[2:17]
	ds_read2_b64 v[78:81], v77 offset0:196 offset1:198
	s_waitcnt lgkmcnt(0)
	v_mfma_f32_32x32x16_bf16 v[34:49], v[78:81], v[66:69], v[34:49]
	ds_read2_b64 v[78:81], v77 offset0:200 offset1:202
	s_waitcnt lgkmcnt(0)
	v_mfma_f32_32x32x16_bf16 v[34:49], v[78:81], v[66:69], v[34:49]
	ds_read2_b64 v[78:81], v77 offset0:204 offset1:206
	s_waitcnt lgkmcnt(0)
	v_mfma_f32_32x32x16_bf16 v[34:49], v[78:81], v[66:69], v[34:49]
	v_add_u32_e32 v75, 0x9000, v75
	ds_read2_b64 v[78:81], v75 offset0:224 offset1:226
	s_waitcnt lgkmcnt(0)
	v_mfma_f32_32x32x16_bf16 v[2:17], v[78:81], v[70:73], v[2:17]
	ds_read2_b64 v[70:73], v75 offset0:228 offset1:230
	s_waitcnt lgkmcnt(0)
	v_mfma_f32_32x32x16_bf16 v[2:17], v[70:73], v[66:69], v[2:17]
	ds_read2_b64 v[70:73], v75 offset0:232 offset1:234
	s_waitcnt lgkmcnt(0)
	v_mfma_f32_32x32x16_bf16 v[2:17], v[70:73], v[66:69], v[2:17]
	ds_read2_b64 v[70:73], v75 offset0:236 offset1:238
	s_waitcnt lgkmcnt(0)
	v_mfma_f32_32x32x16_bf16 v[2:17], v[70:73], v[66:69], v[2:17]
	s_branch .LBB0_1852
